# write-through stores ahead of full barriers + P3 tile-type permutation v2 + attention main-loop cleanup (dead zero-adds, pads, m0 save/restore removed)
# speedup vs baseline: 1.0061x; 1.0005x over previous
.LBB0_1163:
	s_mov_b32 s24, s39
	s_mov_b32 s25, s38
	v_lshl_add_u64 v[118:119], v[146:147], 0, s[10:11]
	s_add_i32 s27, s33, s35
	s_mov_b32 m0, s27
	s_nop 0
	global_load_lds_dwordx4 v[118:119], off
	v_lshl_add_u64 v[118:119], v[148:149], 0, s[6:7]
	s_add_i32 s27, s39, s34
	s_mov_b32 m0, s27
	s_nop 0
	global_load_lds_dwordx4 v[118:119], off
	v_add_u32_e32 v156, s33, v3
	ds_read_b64_tr_b16 v[152:153], v156 offset:32768
	ds_read_b64_tr_b16 v[154:155], v156 offset:33280
	v_add_f32_e32 v118, v98, v99
	v_add_f32_e32 v118, v100, v118
	v_add_f32_e32 v118, v101, v118
	v_add_f32_e32 v118, v102, v118
	v_add_f32_e32 v118, v103, v118
	v_cvt_pk_bf16_f32 v178, v98, v99
	v_cvt_pk_bf16_f32 v179, v100, v101
	s_waitcnt lgkmcnt(9)
	v_mfma_f32_32x32x16_bf16 v[130:145], v[114:117], v[182:185], v[66:81]
	ds_read_b64_tr_b16 v[98:99], v156 offset:36864
	ds_read_b64_tr_b16 v[100:101], v156 offset:37376
	v_add_f32_e32 v114, v104, v118
	v_add_f32_e32 v114, v105, v114
	v_add_f32_e32 v114, v106, v114
	v_add_f32_e32 v157, v107, v114
	s_waitcnt lgkmcnt(10)
	v_mfma_f32_32x32x16_bf16 v[114:129], v[210:213], v[182:185], v[66:81]
	v_cvt_pk_bf16_f32 v180, v102, v103
	v_cvt_pk_bf16_f32 v181, v104, v105
	ds_read_b64_tr_b16 v[102:103], v156 offset:33792
	ds_read_b64_tr_b16 v[104:105], v156 offset:34304
	v_add_f32_e32 v157, v108, v157
	v_add_f32_e32 v157, v109, v157
	v_add_f32_e32 v157, v110, v157
	v_add_f32_e32 v157, v111, v157
	v_cvt_pk_bf16_f32 v170, v106, v107
	v_cvt_pk_bf16_f32 v171, v108, v109
	s_waitcnt lgkmcnt(11)
	v_mfma_f32_32x32x16_bf16 v[130:145], v[206:209], v[174:177], v[130:145]
	ds_read_b64_tr_b16 v[106:107], v156 offset:37888
	ds_read_b64_tr_b16 v[108:109], v156 offset:38400
	s_waitcnt lgkmcnt(12)
	v_mfma_f32_32x32x16_bf16 v[114:129], v[202:205], v[174:177], v[114:129]
	v_add_f32_e32 v157, v112, v157
	v_add_f32_e32 v157, v113, v157
	v_add_f32_e32 v157, v82, v157
	v_add_f32_e32 v157, v83, v157
	v_cvt_pk_bf16_f32 v172, v110, v111
	v_cvt_pk_bf16_f32 v173, v112, v113
	ds_read_b64_tr_b16 v[110:111], v156 offset:34816
	ds_read_b64_tr_b16 v[112:113], v156 offset:35328
	v_add_f32_e32 v157, v84, v157
	v_add_f32_e32 v157, v85, v157
	v_add_f32_e32 v157, v86, v157
	v_add_f32_e32 v157, v87, v157
	v_cvt_pk_bf16_f32 v166, v82, v83
	v_cvt_pk_bf16_f32 v167, v84, v85
	s_waitcnt lgkmcnt(13)
	v_mfma_f32_32x32x16_bf16 v[130:145], v[198:201], v[12:15], v[130:145]
	ds_read_b64_tr_b16 v[82:83], v156 offset:38912
	ds_read_b64_tr_b16 v[84:85], v156 offset:39424
	s_waitcnt lgkmcnt(14)
	v_mfma_f32_32x32x16_bf16 v[114:129], v[194:197], v[12:15], v[114:129]
	v_add_f32_e32 v157, v88, v157
	v_add_f32_e32 v157, v89, v157
	v_add_f32_e32 v157, v90, v157
	v_add_f32_e32 v157, v91, v157
	v_cvt_pk_bf16_f32 v168, v86, v87
	v_cvt_pk_bf16_f32 v169, v88, v89
	ds_read_b64_tr_b16 v[86:87], v156 offset:35840
	ds_read_b64_tr_b16 v[88:89], v156 offset:36352
	v_add_f32_e32 v157, v92, v157
	v_add_f32_e32 v157, v93, v157
	v_add_f32_e32 v157, v94, v157
	v_add_f32_e32 v157, v95, v157
	v_cvt_pk_bf16_f32 v162, v90, v91
	v_cvt_pk_bf16_f32 v163, v92, v93
	s_waitcnt lgkmcnt(14)
	v_mfma_f32_32x32x16_bf16 v[130:145], v[190:193], v[8:11], v[130:145]
	ds_read_b64_tr_b16 v[90:91], v156 offset:39936
	ds_read_b64_tr_b16 v[92:93], v156 offset:40448
	v_mfma_f32_32x32x16_bf16 v[114:129], v[186:189], v[8:11], v[114:129]
	v_add_f32_e32 v156, v96, v157
	v_add_f32_e32 v156, v97, v156
	v_cvt_pk_bf16_f32 v164, v94, v95
	v_cvt_pk_bf16_f32 v165, v96, v97
	v_add_f32_e32 v160, v219, v156
	s_waitcnt lgkmcnt(14)
	v_mfma_f32_32x32x16_bf16 v[34:49], v[178:181], v[152:155], v[34:49]
	v_exp_f32_e32 v130, v130
	v_exp_f32_e32 v131, v131
	v_exp_f32_e32 v132, v132
	v_exp_f32_e32 v133, v133
	s_waitcnt lgkmcnt(12)
	v_mfma_f32_32x32x16_bf16 v[50:65], v[178:181], v[98:101], v[50:65]
	v_exp_f32_e32 v134, v134
	v_exp_f32_e32 v135, v135
	v_exp_f32_e32 v136, v136
	v_exp_f32_e32 v137, v137
	v_add_u32_e32 v98, s24, v7
	ds_read_b128 v[94:97], v98
	ds_read_b128 v[152:155], v98 offset:512
	s_waitcnt lgkmcnt(12)
	v_mfma_f32_32x32x16_bf16 v[34:49], v[170:173], v[102:105], v[34:49]
	v_exp_f32_e32 v138, v138
	v_exp_f32_e32 v139, v139
	v_exp_f32_e32 v140, v140
	v_exp_f32_e32 v141, v141
	ds_read_b128 v[156:159], v98 offset:2048
	ds_read_b128 v[186:189], v98 offset:2560
	s_waitcnt lgkmcnt(12)
	v_mfma_f32_32x32x16_bf16 v[50:65], v[170:173], v[106:109], v[50:65]
	v_exp_f32_e32 v142, v142
	v_exp_f32_e32 v143, v143
	v_exp_f32_e32 v144, v144
	v_exp_f32_e32 v145, v145
	ds_read_b128 v[190:193], v98 offset:4096
	ds_read_b128 v[194:197], v98 offset:4608
	s_waitcnt lgkmcnt(12)
	v_mfma_f32_32x32x16_bf16 v[34:49], v[166:169], v[110:113], v[34:49]
	v_exp_f32_e32 v114, v114
	v_exp_f32_e32 v115, v115
	v_exp_f32_e32 v116, v116
	v_exp_f32_e32 v117, v117
	ds_read_b128 v[198:201], v98 offset:6144
	ds_read_b128 v[202:205], v98 offset:6656
	s_waitcnt lgkmcnt(12)
	v_mfma_f32_32x32x16_bf16 v[50:65], v[166:169], v[82:85], v[50:65]
	v_exp_f32_e32 v118, v118
	v_exp_f32_e32 v119, v119
	v_exp_f32_e32 v120, v120
	v_exp_f32_e32 v121, v121
	s_waitcnt lgkmcnt(10)
	v_mfma_f32_32x32x16_bf16 v[34:49], v[162:165], v[86:89], v[34:49]
	v_exp_f32_e32 v122, v122
	v_exp_f32_e32 v123, v123
	v_exp_f32_e32 v124, v124
	v_exp_f32_e32 v125, v125
	s_waitcnt lgkmcnt(8)
	v_mfma_f32_32x32x16_bf16 v[50:65], v[162:165], v[90:93], v[50:65]
	v_exp_f32_e32 v126, v126
	v_exp_f32_e32 v127, v127
	v_exp_f32_e32 v128, v128
	v_exp_f32_e32 v129, v129
	s_add_i32 s27, s39, 0x2000
	s_cmpk_lg_i32 s39, 0x6000
	s_cselect_b32 s38, s27, 0
	v_lshl_add_u64 v[82:83], v[146:147], 0, s[12:13]
	s_add_i32 s27, s25, s35
	s_mov_b32 m0, s27
	s_nop 0
	global_load_lds_dwordx4 v[82:83], off
	v_lshl_add_u64 v[148:149], v[148:149], 0, s[8:9]
	s_add_i32 s27, s38, s34
	s_mov_b32 m0, s27
	s_nop 0
	global_load_lds_dwordx4 v[148:149], off
	v_add_u32_e32 v161, s25, v3
	ds_read_b64_tr_b16 v[206:207], v161 offset:32768
	ds_read_b64_tr_b16 v[208:209], v161 offset:33280
	s_waitcnt lgkmcnt(9)
	v_mfma_f32_32x32x16_bf16 v[98:113], v[94:97], v[182:185], v[66:81]
	v_add_f32_e32 v82, v130, v131
	v_add_f32_e32 v82, v132, v82
	v_add_f32_e32 v82, v133, v82
	v_add_f32_e32 v82, v134, v82
	v_add_f32_e32 v82, v135, v82
	v_cvt_pk_bf16_f32 v178, v130, v131
	v_cvt_pk_bf16_f32 v179, v132, v133
	ds_read_b64_tr_b16 v[130:131], v161 offset:36864
	ds_read_b64_tr_b16 v[132:133], v161 offset:37376
	v_add_f32_e32 v82, v136, v82
	v_add_f32_e32 v82, v137, v82
	v_add_f32_e32 v82, v138, v82
	v_add_f32_e32 v162, v139, v82
	s_waitcnt lgkmcnt(10)
	v_mfma_f32_32x32x16_bf16 v[82:97], v[152:155], v[182:185], v[66:81]
	v_cvt_pk_bf16_f32 v180, v134, v135
	v_cvt_pk_bf16_f32 v181, v136, v137
	ds_read_b64_tr_b16 v[134:135], v161 offset:33792
	ds_read_b64_tr_b16 v[136:137], v161 offset:34304
	s_waitcnt lgkmcnt(11)
	v_mfma_f32_32x32x16_bf16 v[98:113], v[156:159], v[174:177], v[98:113]
	v_add_f32_e32 v152, v140, v162
	v_add_f32_e32 v152, v141, v152
	v_add_f32_e32 v152, v142, v152
	v_add_f32_e32 v152, v143, v152
	v_cvt_pk_bf16_f32 v170, v138, v139
	v_cvt_pk_bf16_f32 v171, v140, v141
	ds_read_b64_tr_b16 v[138:139], v161 offset:37888
	ds_read_b64_tr_b16 v[140:141], v161 offset:38400
	s_waitcnt lgkmcnt(12)
	v_mfma_f32_32x32x16_bf16 v[82:97], v[186:189], v[174:177], v[82:97]
	v_add_f32_e32 v152, v144, v152
	v_add_f32_e32 v152, v145, v152
	v_add_f32_e32 v152, v114, v152
	v_add_f32_e32 v152, v115, v152
	v_cvt_pk_bf16_f32 v172, v142, v143
	v_cvt_pk_bf16_f32 v173, v144, v145
	ds_read_b64_tr_b16 v[142:143], v161 offset:34816
	ds_read_b64_tr_b16 v[144:145], v161 offset:35328
	s_waitcnt lgkmcnt(13)
	v_mfma_f32_32x32x16_bf16 v[98:113], v[190:193], v[12:15], v[98:113]
	v_add_f32_e32 v152, v116, v152
	v_add_f32_e32 v152, v117, v152
	v_add_f32_e32 v152, v118, v152
	v_add_f32_e32 v156, v119, v152
	v_cvt_pk_bf16_f32 v166, v114, v115
	v_cvt_pk_bf16_f32 v167, v116, v117
	ds_read_b64_tr_b16 v[152:153], v161 offset:38912
	ds_read_b64_tr_b16 v[154:155], v161 offset:39424
	s_waitcnt lgkmcnt(14)
	v_mfma_f32_32x32x16_bf16 v[82:97], v[194:197], v[12:15], v[82:97]
	v_add_f32_e32 v114, v120, v156
	v_add_f32_e32 v114, v121, v114
	v_add_f32_e32 v114, v122, v114
	v_add_f32_e32 v114, v123, v114
	v_cvt_pk_bf16_f32 v168, v118, v119
	v_cvt_pk_bf16_f32 v169, v120, v121
	ds_read_b64_tr_b16 v[118:119], v161 offset:35840
	ds_read_b64_tr_b16 v[120:121], v161 offset:36352
	s_waitcnt lgkmcnt(14)
	v_mfma_f32_32x32x16_bf16 v[98:113], v[198:201], v[8:11], v[98:113]
	v_add_f32_e32 v114, v124, v114
	v_add_f32_e32 v114, v125, v114
	v_add_f32_e32 v114, v126, v114
	v_add_f32_e32 v114, v127, v114
	v_cvt_pk_bf16_f32 v162, v122, v123
	v_cvt_pk_bf16_f32 v163, v124, v125
	ds_read_b64_tr_b16 v[122:123], v161 offset:39936
	ds_read_b64_tr_b16 v[124:125], v161 offset:40448
	v_mfma_f32_32x32x16_bf16 v[82:97], v[202:205], v[8:11], v[82:97]
	v_add_f32_e32 v114, v128, v114
	v_add_f32_e32 v114, v129, v114
	v_cvt_pk_bf16_f32 v164, v126, v127
	v_cvt_pk_bf16_f32 v165, v128, v129
	v_add_f32_e32 v219, v160, v114
	s_waitcnt lgkmcnt(14)
	v_mfma_f32_32x32x16_bf16 v[34:49], v[178:181], v[206:209], v[34:49]
	v_exp_f32_e32 v98, v98
	v_exp_f32_e32 v99, v99
	v_exp_f32_e32 v100, v100
	v_exp_f32_e32 v101, v101
	s_waitcnt lgkmcnt(12)
	v_mfma_f32_32x32x16_bf16 v[50:65], v[178:181], v[130:133], v[50:65]
	v_exp_f32_e32 v102, v102
	v_exp_f32_e32 v103, v103
	v_exp_f32_e32 v104, v104
	v_exp_f32_e32 v105, v105
	v_add_u32_e32 v126, s38, v7
	ds_read_b128 v[114:117], v126
	ds_read_b128 v[210:213], v126 offset:512
	s_waitcnt lgkmcnt(12)
	v_mfma_f32_32x32x16_bf16 v[34:49], v[170:173], v[134:137], v[34:49]
	v_exp_f32_e32 v106, v106
	v_exp_f32_e32 v107, v107
	v_exp_f32_e32 v108, v108
	v_exp_f32_e32 v109, v109
	ds_read_b128 v[206:209], v126 offset:2048
	ds_read_b128 v[202:205], v126 offset:2560
	s_waitcnt lgkmcnt(12)
	v_mfma_f32_32x32x16_bf16 v[50:65], v[170:173], v[138:141], v[50:65]
	v_exp_f32_e32 v110, v110
	v_exp_f32_e32 v111, v111
	v_exp_f32_e32 v112, v112
	v_exp_f32_e32 v113, v113
	ds_read_b128 v[198:201], v126 offset:4096
	ds_read_b128 v[194:197], v126 offset:4608
	s_waitcnt lgkmcnt(12)
	v_mfma_f32_32x32x16_bf16 v[34:49], v[166:169], v[142:145], v[34:49]
	v_exp_f32_e32 v82, v82
	v_exp_f32_e32 v83, v83
	v_exp_f32_e32 v84, v84
	v_exp_f32_e32 v85, v85
	ds_read_b128 v[190:193], v126 offset:6144
	ds_read_b128 v[186:189], v126 offset:6656
	s_waitcnt lgkmcnt(12)
	v_mfma_f32_32x32x16_bf16 v[50:65], v[166:169], v[152:155], v[50:65]
	v_exp_f32_e32 v86, v86
	v_exp_f32_e32 v87, v87
	v_exp_f32_e32 v88, v88
	v_exp_f32_e32 v89, v89
	s_waitcnt lgkmcnt(10)
	v_mfma_f32_32x32x16_bf16 v[34:49], v[162:165], v[118:121], v[34:49]
	v_exp_f32_e32 v90, v90
	v_exp_f32_e32 v91, v91
	v_exp_f32_e32 v92, v92
	v_exp_f32_e32 v93, v93
	s_waitcnt lgkmcnt(8)
	v_mfma_f32_32x32x16_bf16 v[50:65], v[162:165], v[122:125], v[50:65]
	v_exp_f32_e32 v94, v94
	v_exp_f32_e32 v95, v95
	v_exp_f32_e32 v96, v96
	v_exp_f32_e32 v97, v97
	s_add_i32 s25, s38, 0x2000
	s_waitcnt vmcnt(0) lgkmcnt(0)
	s_barrier
	s_cmpk_lg_i32 s38, 0x6000
	s_cselect_b32 s39, s25, 0
	s_add_i32 s37, s37, 2
	v_lshl_add_u64 v[146:147], v[146:147], 0, s[8:9]
	s_cmpk_gt_u32 s37, 0xf9
	s_mov_b32 s33, s24
	s_cbranch_scc0 .LBB0_1163
	s_and_b32 s25, s36, 0x3fffffc0
	s_cmp_lg_u32 0, -1
	s_cselect_b32 s27, 0, 0
	s_add_i32 s27, s27, 0x8000
	s_lshl_b32 s25, s25, 2
	v_add3_u32 v218, v151, s27, v150
	s_add_i32 s27, s25, 0
	s_add_i32 s27, s27, 0x10000
	v_lshl_add_u64 v[16:17], v[16:17], 0, s[14:15]
	s_add_i32 s25, s24, s35
	s_mov_b32 s28, m0
	s_mov_b32 m0, s25
	s_nop 0
	global_load_lds_dwordx4 v[16:17], off
	s_mov_b32 m0, s28
	v_lshl_add_u64 v[16:17], v[4:5], 0, s[16:17]
	s_add_i32 s25, s39, s34
	s_mov_b32 s28, m0
	s_mov_b32 m0, s25
	s_nop 0
	global_load_lds_dwordx4 v[16:17], off
	s_mov_b32 m0, s28
	v_add_u32_e32 v16, s24, v3
	ds_read_b64_tr_b16 v[130:131], v16 offset:32768
	ds_read_b64_tr_b16 v[132:133], v16 offset:33280
	v_add_f32_e32 v17, v98, v99
	v_add_f32_e32 v17, v100, v17
	v_add_f32_e32 v17, v101, v17
	v_add_f32_e32 v17, v102, v17
	v_add_f32_e32 v17, v103, v17
	v_cvt_pk_bf16_f32 v178, v98, v99
	v_cvt_pk_bf16_f32 v179, v100, v101
	s_waitcnt lgkmcnt(9)
	v_mfma_f32_32x32x16_bf16 v[146:161], v[114:117], v[182:185], v[66:81]
	ds_read_b64_tr_b16 v[98:99], v16 offset:36864
	ds_read_b64_tr_b16 v[100:101], v16 offset:37376
	v_add_f32_e32 v17, v104, v17
	v_add_f32_e32 v17, v105, v17
	v_add_f32_e32 v17, v106, v17
	v_add_f32_e32 v17, v107, v17
	v_cvt_pk_bf16_f32 v180, v102, v103
	v_cvt_pk_bf16_f32 v181, v104, v105
	s_waitcnt lgkmcnt(10)
	v_mfma_f32_32x32x16_bf16 v[114:129], v[210:213], v[182:185], v[66:81]
	ds_read_b64_tr_b16 v[102:103], v16 offset:33792
	ds_read_b64_tr_b16 v[104:105], v16 offset:34304
	v_add_f32_e32 v17, v108, v17
	v_add_f32_e32 v17, v109, v17
	v_add_f32_e32 v17, v110, v17
	v_add_f32_e32 v17, v111, v17
	v_cvt_pk_bf16_f32 v170, v106, v107
	v_cvt_pk_bf16_f32 v171, v108, v109
	s_waitcnt lgkmcnt(11)
	v_mfma_f32_32x32x16_bf16 v[146:161], v[206:209], v[174:177], v[146:161]
	ds_read_b64_tr_b16 v[106:107], v16 offset:37888
	ds_read_b64_tr_b16 v[108:109], v16 offset:38400
	v_add_f32_e32 v17, v112, v17
	v_add_f32_e32 v17, v113, v17
	v_add_f32_e32 v17, v82, v17
	v_add_f32_e32 v17, v83, v17
	v_cvt_pk_bf16_f32 v172, v110, v111
	v_cvt_pk_bf16_f32 v173, v112, v113
	s_waitcnt lgkmcnt(12)
	v_mfma_f32_32x32x16_bf16 v[114:129], v[202:205], v[174:177], v[114:129]
	ds_read_b64_tr_b16 v[110:111], v16 offset:34816
	ds_read_b64_tr_b16 v[112:113], v16 offset:35328
	v_add_f32_e32 v17, v84, v17
	v_add_f32_e32 v17, v85, v17
	v_add_f32_e32 v17, v86, v17
	v_add_f32_e32 v17, v87, v17
	v_cvt_pk_bf16_f32 v166, v82, v83
	v_cvt_pk_bf16_f32 v167, v84, v85
	s_waitcnt lgkmcnt(13)
	v_mfma_f32_32x32x16_bf16 v[146:161], v[198:201], v[12:15], v[146:161]
	ds_read_b64_tr_b16 v[82:83], v16 offset:38912
	ds_read_b64_tr_b16 v[84:85], v16 offset:39424
	v_add_f32_e32 v17, v88, v17
	v_add_f32_e32 v17, v89, v17
	v_add_f32_e32 v17, v90, v17
	v_add_f32_e32 v17, v91, v17
	v_cvt_pk_bf16_f32 v168, v86, v87
	v_cvt_pk_bf16_f32 v169, v88, v89
	s_waitcnt lgkmcnt(14)
	v_mfma_f32_32x32x16_bf16 v[114:129], v[194:197], v[12:15], v[114:129]
	ds_read_b64_tr_b16 v[86:87], v16 offset:35840
	ds_read_b64_tr_b16 v[88:89], v16 offset:36352
	v_add_f32_e32 v17, v92, v17
	v_add_f32_e32 v17, v93, v17
	v_add_f32_e32 v17, v94, v17
	v_add_f32_e32 v17, v95, v17
	v_cvt_pk_bf16_f32 v162, v90, v91
	v_cvt_pk_bf16_f32 v163, v92, v93
	s_waitcnt lgkmcnt(14)
	v_mfma_f32_32x32x16_bf16 v[146:161], v[190:193], v[8:11], v[146:161]
	ds_read_b64_tr_b16 v[90:91], v16 offset:39936
	ds_read_b64_tr_b16 v[92:93], v16 offset:40448
	v_add_f32_e32 v16, v96, v17
	v_add_f32_e32 v16, v97, v16
	v_add_f32_e32 v16, 0, v16
	v_cvt_pk_bf16_f32 v164, v94, v95
	v_cvt_pk_bf16_f32 v165, v96, v97
	v_mfma_f32_32x32x16_bf16 v[114:129], v[186:189], v[8:11], v[114:129]
	v_add_f32_e32 v202, v219, v16
	s_waitcnt lgkmcnt(14)
	v_mfma_f32_32x32x16_bf16 v[34:49], v[178:181], v[130:133], v[34:49]
	s_nop 0
	v_exp_f32_e32 v146, v146
	v_exp_f32_e32 v147, v147
	v_exp_f32_e32 v148, v148
	v_exp_f32_e32 v149, v149
	s_waitcnt lgkmcnt(12)
	v_mfma_f32_32x32x16_bf16 v[50:65], v[178:181], v[98:101], v[50:65]
	v_exp_f32_e32 v150, v150
	v_exp_f32_e32 v151, v151
	v_exp_f32_e32 v152, v152
	v_exp_f32_e32 v153, v153
	v_add_u32_e32 v16, s39, v7
	ds_read_b128 v[94:97], v16
	ds_read_b128 v[98:101], v16 offset:512
	s_waitcnt lgkmcnt(12)
	v_mfma_f32_32x32x16_bf16 v[34:49], v[170:173], v[102:105], v[34:49]
	v_exp_f32_e32 v154, v154
	v_exp_f32_e32 v155, v155
	v_exp_f32_e32 v156, v156
	v_exp_f32_e32 v157, v157
	ds_read_b128 v[102:105], v16 offset:2048
	ds_read_b128 v[186:189], v16 offset:2560
	s_waitcnt lgkmcnt(12)
	v_mfma_f32_32x32x16_bf16 v[50:65], v[170:173], v[106:109], v[50:65]
	v_exp_f32_e32 v158, v158
	v_exp_f32_e32 v159, v159
	v_exp_f32_e32 v160, v160
	v_exp_f32_e32 v161, v161
	ds_read_b128 v[106:109], v16 offset:4096
	ds_read_b128 v[190:193], v16 offset:4608
	s_waitcnt lgkmcnt(12)
	v_mfma_f32_32x32x16_bf16 v[34:49], v[166:169], v[110:113], v[34:49]
	v_exp_f32_e32 v114, v114
	v_exp_f32_e32 v115, v115
	v_exp_f32_e32 v116, v116
	v_exp_f32_e32 v117, v117
	ds_read_b128 v[110:113], v16 offset:6144
	ds_read_b128 v[194:197], v16 offset:6656
	s_waitcnt lgkmcnt(12)
	v_mfma_f32_32x32x16_bf16 v[50:65], v[166:169], v[82:85], v[50:65]
	v_exp_f32_e32 v118, v118
	v_exp_f32_e32 v119, v119
	v_exp_f32_e32 v120, v120
	v_exp_f32_e32 v121, v121
	s_waitcnt lgkmcnt(10)
	v_mfma_f32_32x32x16_bf16 v[34:49], v[162:165], v[86:89], v[34:49]
	v_exp_f32_e32 v122, v122
	v_exp_f32_e32 v123, v123
	v_exp_f32_e32 v124, v124
	v_exp_f32_e32 v125, v125
	s_waitcnt lgkmcnt(8)
	v_mfma_f32_32x32x16_bf16 v[50:65], v[162:165], v[90:93], v[50:65]
	v_exp_f32_e32 v126, v126
	v_exp_f32_e32 v127, v127
	v_exp_f32_e32 v128, v128
	v_exp_f32_e32 v129, v129
	s_add_i32 s24, s39, 0x2000
	s_cmpk_lg_i32 s39, 0x6000
	s_cselect_b32 s25, s24, 0
	v_lshl_add_u64 v[16:17], v[4:5], 0, s[20:21]
	s_add_i32 s24, s25, s34
	s_mov_b32 s28, m0
	s_mov_b32 m0, s24
	s_nop 0
	global_load_lds_dwordx4 v[16:17], off
	s_mov_b32 m0, s28
	v_add_u32_e32 v16, s38, v3
	ds_read_b64_tr_b16 v[198:199], v16 offset:32768
	ds_read_b64_tr_b16 v[200:201], v16 offset:33280
	v_add_f32_e32 v17, v146, v147
	v_add_f32_e32 v17, v148, v17
	v_add_f32_e32 v17, v149, v17
	v_add_f32_e32 v17, v150, v17
	v_add_f32_e32 v17, v151, v17
	v_cvt_pk_bf16_f32 v178, v146, v147
	v_cvt_pk_bf16_f32 v179, v148, v149
	s_waitcnt lgkmcnt(9)
	v_mfma_f32_32x32x16_bf16 v[130:145], v[94:97], v[182:185], v[66:81]
	ds_read_b64_tr_b16 v[146:147], v16 offset:36864
	ds_read_b64_tr_b16 v[148:149], v16 offset:37376
	v_add_f32_e32 v17, v152, v17
	v_add_f32_e32 v17, v153, v17
	v_add_f32_e32 v17, v154, v17
	v_add_f32_e32 v17, v155, v17
	v_cvt_pk_bf16_f32 v180, v150, v151
	v_cvt_pk_bf16_f32 v181, v152, v153
	s_waitcnt lgkmcnt(10)
	v_mfma_f32_32x32x16_bf16 v[82:97], v[98:101], v[182:185], v[66:81]
	ds_read_b64_tr_b16 v[98:99], v16 offset:33792
	ds_read_b64_tr_b16 v[100:101], v16 offset:34304
	v_add_f32_e32 v17, v156, v17
	v_add_f32_e32 v17, v157, v17
	v_add_f32_e32 v17, v158, v17
	v_add_f32_e32 v17, v159, v17
	v_cvt_pk_bf16_f32 v170, v154, v155
	v_cvt_pk_bf16_f32 v171, v156, v157
	s_waitcnt lgkmcnt(11)
	v_mfma_f32_32x32x16_bf16 v[130:145], v[102:105], v[174:177], v[130:145]
	ds_read_b64_tr_b16 v[102:103], v16 offset:37888
	ds_read_b64_tr_b16 v[104:105], v16 offset:38400
	v_add_f32_e32 v17, v160, v17
	v_add_f32_e32 v17, v161, v17
	v_add_f32_e32 v17, v114, v17
	v_add_f32_e32 v17, v115, v17
	v_cvt_pk_bf16_f32 v172, v158, v159
	v_cvt_pk_bf16_f32 v173, v160, v161
	s_waitcnt lgkmcnt(12)
	v_mfma_f32_32x32x16_bf16 v[82:97], v[186:189], v[174:177], v[82:97]
	ds_read_b64_tr_b16 v[150:151], v16 offset:34816
	ds_read_b64_tr_b16 v[152:153], v16 offset:35328
	v_add_f32_e32 v17, v116, v17
	v_add_f32_e32 v17, v117, v17
	v_add_f32_e32 v17, v118, v17
	v_add_f32_e32 v17, v119, v17
	v_cvt_pk_bf16_f32 v166, v114, v115
	v_cvt_pk_bf16_f32 v167, v116, v117
	s_waitcnt lgkmcnt(13)
	v_mfma_f32_32x32x16_bf16 v[130:145], v[106:109], v[12:15], v[130:145]
	ds_read_b64_tr_b16 v[106:107], v16 offset:38912
	ds_read_b64_tr_b16 v[108:109], v16 offset:39424
	v_add_f32_e32 v17, v120, v17
	v_add_f32_e32 v17, v121, v17
	v_add_f32_e32 v17, v122, v17
	v_add_f32_e32 v17, v123, v17
	v_cvt_pk_bf16_f32 v168, v118, v119
	v_cvt_pk_bf16_f32 v169, v120, v121
	s_waitcnt lgkmcnt(14)
	v_mfma_f32_32x32x16_bf16 v[82:97], v[190:193], v[12:15], v[82:97]
	ds_read_b64_tr_b16 v[114:115], v16 offset:35840
	ds_read_b64_tr_b16 v[116:117], v16 offset:36352
	v_add_f32_e32 v17, v124, v17
	v_add_f32_e32 v17, v125, v17
	v_add_f32_e32 v17, v126, v17
	v_add_f32_e32 v17, v127, v17
	v_cvt_pk_bf16_f32 v162, v122, v123
	v_cvt_pk_bf16_f32 v163, v124, v125
	s_waitcnt lgkmcnt(14)
	v_mfma_f32_32x32x16_bf16 v[130:145], v[110:113], v[8:11], v[130:145]
	ds_read_b64_tr_b16 v[110:111], v16 offset:39936
	ds_read_b64_tr_b16 v[112:113], v16 offset:40448
	v_add_f32_e32 v16, v128, v17
	v_add_f32_e32 v16, v129, v16
	v_add_f32_e32 v16, 0, v16
	v_cvt_pk_bf16_f32 v164, v126, v127
	v_cvt_pk_bf16_f32 v165, v128, v129
	v_mfma_f32_32x32x16_bf16 v[82:97], v[194:197], v[8:11], v[82:97]
	v_add_f32_e32 v16, v202, v16
	s_waitcnt lgkmcnt(14)
	v_mfma_f32_32x32x16_bf16 v[34:49], v[178:181], v[198:201], v[34:49]
	s_nop 0
	v_exp_f32_e32 v130, v130
	v_exp_f32_e32 v131, v131
	v_exp_f32_e32 v132, v132
	v_exp_f32_e32 v133, v133
	s_waitcnt lgkmcnt(12)
	v_mfma_f32_32x32x16_bf16 v[50:65], v[178:181], v[146:149], v[50:65]
	v_exp_f32_e32 v134, v134
	v_exp_f32_e32 v135, v135
	v_exp_f32_e32 v136, v136
	v_exp_f32_e32 v137, v137
	v_add_u32_e32 v17, s25, v7
	ds_read_b128 v[146:149], v17
	ds_read_b128 v[154:157], v17 offset:512
	s_waitcnt lgkmcnt(12)
	v_mfma_f32_32x32x16_bf16 v[34:49], v[170:173], v[98:101], v[34:49]
	v_exp_f32_e32 v138, v138
	v_exp_f32_e32 v139, v139
	v_exp_f32_e32 v140, v140
	v_exp_f32_e32 v141, v141
	ds_read_b128 v[158:161], v17 offset:2048
	ds_read_b128 v[186:189], v17 offset:2560
	s_waitcnt lgkmcnt(12)
	v_mfma_f32_32x32x16_bf16 v[50:65], v[170:173], v[102:105], v[50:65]
	v_exp_f32_e32 v142, v142
	v_exp_f32_e32 v143, v143
	v_exp_f32_e32 v144, v144
	v_exp_f32_e32 v145, v145
	ds_read_b128 v[190:193], v17 offset:4096
	ds_read_b128 v[194:197], v17 offset:4608
	s_waitcnt lgkmcnt(12)
	v_mfma_f32_32x32x16_bf16 v[34:49], v[166:169], v[150:153], v[34:49]
	v_exp_f32_e32 v82, v82
	v_exp_f32_e32 v83, v83
	v_exp_f32_e32 v84, v84
	v_exp_f32_e32 v85, v85
	ds_read_b128 v[150:153], v17 offset:6144
	ds_read_b128 v[198:201], v17 offset:6656
	s_waitcnt lgkmcnt(12)
	v_mfma_f32_32x32x16_bf16 v[50:65], v[166:169], v[106:109], v[50:65]
	v_exp_f32_e32 v86, v86
	v_exp_f32_e32 v87, v87
	v_exp_f32_e32 v88, v88
	v_exp_f32_e32 v89, v89
	s_waitcnt lgkmcnt(10)
	v_mfma_f32_32x32x16_bf16 v[34:49], v[162:165], v[114:117], v[34:49]
	v_exp_f32_e32 v90, v90
	v_exp_f32_e32 v91, v91
	v_exp_f32_e32 v92, v92
	v_exp_f32_e32 v93, v93
	s_waitcnt lgkmcnt(8)
	v_mfma_f32_32x32x16_bf16 v[50:65], v[162:165], v[110:113], v[50:65]
	v_exp_f32_e32 v94, v94
	v_exp_f32_e32 v95, v95
	v_exp_f32_e32 v96, v96
	v_exp_f32_e32 v97, v97
	s_waitcnt vmcnt(0) lgkmcnt(0)
	s_barrier
	s_add_i32 s24, s25, 0x2000
	s_cmpk_lg_i32 s25, 0x6000
	s_cselect_b32 s24, s24, 0
	v_lshl_add_u64 v[4:5], v[4:5], 0, s[14:15]
	s_add_i32 s28, s24, s34
	s_mov_b32 s29, m0
	s_mov_b32 m0, s28
	s_nop 0
	global_load_lds_dwordx4 v[4:5], off
	s_mov_b32 m0, s29
	v_add_u32_e32 v4, s39, v3
	ds_read_b64_tr_b16 v[202:203], v4 offset:32768
	ds_read_b64_tr_b16 v[204:205], v4 offset:33280
	v_add_f32_e32 v5, v130, v131
	v_add_f32_e32 v5, v132, v5
	v_add_f32_e32 v5, v133, v5
	v_add_f32_e32 v5, v134, v5
	v_add_f32_e32 v5, v135, v5
	v_cvt_pk_bf16_f32 v178, v130, v131
	v_cvt_pk_bf16_f32 v179, v132, v133
	s_waitcnt lgkmcnt(9)
	v_mfma_f32_32x32x16_bf16 v[114:129], v[146:149], v[182:185], v[66:81]
	ds_read_b64_tr_b16 v[130:131], v4 offset:36864
	ds_read_b64_tr_b16 v[132:133], v4 offset:37376
	v_add_f32_e32 v5, v136, v5
	v_add_f32_e32 v5, v137, v5
	v_add_f32_e32 v5, v138, v5
	v_add_f32_e32 v5, v139, v5
	v_cvt_pk_bf16_f32 v180, v134, v135
	v_cvt_pk_bf16_f32 v181, v136, v137
	s_waitcnt lgkmcnt(10)
	v_mfma_f32_32x32x16_bf16 v[98:113], v[154:157], v[182:185], v[66:81]
	ds_read_b64_tr_b16 v[134:135], v4 offset:33792
	ds_read_b64_tr_b16 v[136:137], v4 offset:34304
	v_add_f32_e32 v5, v140, v5
	v_add_f32_e32 v5, v141, v5
	v_add_f32_e32 v5, v142, v5
	v_add_f32_e32 v5, v143, v5
	v_cvt_pk_bf16_f32 v170, v138, v139
	v_cvt_pk_bf16_f32 v171, v140, v141
	s_waitcnt lgkmcnt(11)
	v_mfma_f32_32x32x16_bf16 v[114:129], v[158:161], v[174:177], v[114:129]
	ds_read_b64_tr_b16 v[138:139], v4 offset:37888
	ds_read_b64_tr_b16 v[140:141], v4 offset:38400
	v_add_f32_e32 v5, v144, v5
	v_add_f32_e32 v5, v145, v5
	v_add_f32_e32 v5, v82, v5
	v_add_f32_e32 v5, v83, v5
	v_cvt_pk_bf16_f32 v172, v142, v143
	v_cvt_pk_bf16_f32 v173, v144, v145
	s_waitcnt lgkmcnt(12)
	v_mfma_f32_32x32x16_bf16 v[98:113], v[186:189], v[174:177], v[98:113]
	ds_read_b64_tr_b16 v[142:143], v4 offset:34816
	ds_read_b64_tr_b16 v[144:145], v4 offset:35328
	v_add_f32_e32 v5, v84, v5
	v_add_f32_e32 v5, v85, v5
	v_add_f32_e32 v5, v86, v5
	v_add_f32_e32 v5, v87, v5
	v_cvt_pk_bf16_f32 v166, v82, v83
	v_cvt_pk_bf16_f32 v167, v84, v85
	s_waitcnt lgkmcnt(13)
	v_mfma_f32_32x32x16_bf16 v[114:129], v[190:193], v[12:15], v[114:129]
	ds_read_b64_tr_b16 v[82:83], v4 offset:38912
	ds_read_b64_tr_b16 v[84:85], v4 offset:39424
	v_add_f32_e32 v5, v88, v5
	v_add_f32_e32 v5, v89, v5
	v_add_f32_e32 v5, v90, v5
	v_add_f32_e32 v5, v91, v5
	v_cvt_pk_bf16_f32 v168, v86, v87
	v_cvt_pk_bf16_f32 v169, v88, v89
	s_waitcnt lgkmcnt(14)
	v_mfma_f32_32x32x16_bf16 v[98:113], v[194:197], v[12:15], v[98:113]
	ds_read_b64_tr_b16 v[86:87], v4 offset:35840
	ds_read_b64_tr_b16 v[88:89], v4 offset:36352
	v_add_f32_e32 v5, v92, v5
	v_add_f32_e32 v5, v93, v5
	v_add_f32_e32 v5, v94, v5
	v_add_f32_e32 v5, v95, v5
	v_cvt_pk_bf16_f32 v162, v90, v91
	v_cvt_pk_bf16_f32 v163, v92, v93
	s_waitcnt lgkmcnt(14)
	v_mfma_f32_32x32x16_bf16 v[114:129], v[150:153], v[8:11], v[114:129]
	ds_read_b64_tr_b16 v[90:91], v4 offset:39936
	ds_read_b64_tr_b16 v[92:93], v4 offset:40448
	v_add_f32_e32 v4, v96, v5
	v_add_f32_e32 v4, v97, v4
	v_add_f32_e32 v4, 0, v4
	v_cvt_pk_bf16_f32 v164, v94, v95
	v_cvt_pk_bf16_f32 v165, v96, v97
	v_mfma_f32_32x32x16_bf16 v[98:113], v[198:201], v[8:11], v[98:113]
	v_add_f32_e32 v4, v16, v4
	s_waitcnt lgkmcnt(14)
	v_mfma_f32_32x32x16_bf16 v[34:49], v[178:181], v[202:205], v[34:49]
	s_nop 0
	v_exp_f32_e32 v114, v114
	v_exp_f32_e32 v115, v115
	v_exp_f32_e32 v116, v116
	v_exp_f32_e32 v117, v117
	s_waitcnt lgkmcnt(12)
	v_mfma_f32_32x32x16_bf16 v[50:65], v[178:181], v[130:133], v[50:65]
	v_exp_f32_e32 v118, v118
	v_exp_f32_e32 v119, v119
	v_exp_f32_e32 v120, v120
	v_exp_f32_e32 v121, v121
	v_add_u32_e32 v5, s24, v7
	ds_read_b128 v[94:97], v5
	s_waitcnt lgkmcnt(11)
	v_mfma_f32_32x32x16_bf16 v[34:49], v[170:173], v[134:137], v[34:49]
	v_exp_f32_e32 v122, v122
	v_exp_f32_e32 v123, v123
	v_exp_f32_e32 v124, v124
	v_exp_f32_e32 v125, v125
	ds_read_b128 v[130:133], v5 offset:2048
	s_waitcnt lgkmcnt(10)
	v_mfma_f32_32x32x16_bf16 v[50:65], v[170:173], v[138:141], v[50:65]
	v_exp_f32_e32 v126, v126
	v_exp_f32_e32 v127, v127
	v_exp_f32_e32 v128, v128
	v_exp_f32_e32 v129, v129
	ds_read_b128 v[134:137], v5 offset:4096
	s_waitcnt lgkmcnt(9)
	v_mfma_f32_32x32x16_bf16 v[34:49], v[166:169], v[142:145], v[34:49]
	v_exp_f32_e32 v98, v98
	v_exp_f32_e32 v99, v99
	v_exp_f32_e32 v100, v100
	v_exp_f32_e32 v101, v101
	ds_read_b128 v[138:141], v5 offset:6144
	s_waitcnt lgkmcnt(8)
	v_mfma_f32_32x32x16_bf16 v[50:65], v[166:169], v[82:85], v[50:65]
	v_exp_f32_e32 v102, v102
	v_exp_f32_e32 v103, v103
	v_exp_f32_e32 v104, v104
	v_exp_f32_e32 v105, v105
	s_waitcnt lgkmcnt(6)
	v_mfma_f32_32x32x16_bf16 v[34:49], v[162:165], v[86:89], v[34:49]
	v_exp_f32_e32 v106, v106
	v_exp_f32_e32 v107, v107
	v_exp_f32_e32 v108, v108
	v_exp_f32_e32 v109, v109
	s_waitcnt lgkmcnt(4)
	v_mfma_f32_32x32x16_bf16 v[50:65], v[162:165], v[90:93], v[50:65]
	v_exp_f32_e32 v110, v110
	v_exp_f32_e32 v111, v111
	v_exp_f32_e32 v112, v112
	v_exp_f32_e32 v113, v113
	v_add_u32_e32 v3, s25, v3
	ds_read_b64_tr_b16 v[82:83], v3 offset:32768
	ds_read_b64_tr_b16 v[84:85], v3 offset:33280
	v_add_f32_e32 v5, v114, v115
	v_add_f32_e32 v5, v116, v5
	v_add_f32_e32 v5, v117, v5
	v_add_f32_e32 v5, v118, v5
	v_add_f32_e32 v5, v119, v5
	v_cvt_pk_bf16_f32 v178, v114, v115
	v_cvt_pk_bf16_f32 v179, v116, v117
	s_waitcnt lgkmcnt(5)
	v_mfma_f32_32x32x16_bf16 v[66:81], v[94:97], v[182:185], v[66:81]
	ds_read_b64_tr_b16 v[86:87], v3 offset:36864
	ds_read_b64_tr_b16 v[88:89], v3 offset:37376
	v_add_f32_e32 v5, v120, v5
	v_add_f32_e32 v5, v121, v5
	v_add_f32_e32 v5, v122, v5
	v_add_f32_e32 v5, v123, v5
	v_cvt_pk_bf16_f32 v180, v118, v119
	v_cvt_pk_bf16_f32 v181, v120, v121
	ds_read_b64_tr_b16 v[90:91], v3 offset:33792
	ds_read_b64_tr_b16 v[92:93], v3 offset:34304
	v_add_f32_e32 v5, v124, v5
	v_add_f32_e32 v5, v125, v5
	v_add_f32_e32 v5, v126, v5
	v_add_f32_e32 v5, v127, v5
	v_cvt_pk_bf16_f32 v170, v122, v123
	v_cvt_pk_bf16_f32 v171, v124, v125
	s_waitcnt lgkmcnt(8)
	v_mfma_f32_32x32x16_bf16 v[66:81], v[130:133], v[174:177], v[66:81]
	ds_read_b64_tr_b16 v[94:95], v3 offset:37888
	ds_read_b64_tr_b16 v[96:97], v3 offset:38400
	v_add_f32_e32 v5, v128, v5
	v_add_f32_e32 v5, v129, v5
	v_add_f32_e32 v5, v98, v5
	v_add_f32_e32 v5, v99, v5
	v_cvt_pk_bf16_f32 v172, v126, v127
	v_cvt_pk_bf16_f32 v173, v128, v129
	ds_read_b64_tr_b16 v[114:115], v3 offset:34816
	ds_read_b64_tr_b16 v[116:117], v3 offset:35328
	v_add_f32_e32 v5, v100, v5
	v_add_f32_e32 v5, v101, v5
	v_add_f32_e32 v5, v102, v5
	v_add_f32_e32 v5, v103, v5
	v_cvt_pk_bf16_f32 v166, v98, v99
	v_cvt_pk_bf16_f32 v167, v100, v101
	s_waitcnt lgkmcnt(11)
	v_mfma_f32_32x32x16_bf16 v[66:81], v[134:137], v[12:15], v[66:81]
	ds_read_b64_tr_b16 v[98:99], v3 offset:38912
	ds_read_b64_tr_b16 v[100:101], v3 offset:39424
	v_add_f32_e32 v5, v104, v5
	v_add_f32_e32 v5, v105, v5
	v_add_f32_e32 v5, v106, v5
	v_add_f32_e32 v5, v107, v5
	v_cvt_pk_bf16_f32 v168, v102, v103
	v_cvt_pk_bf16_f32 v169, v104, v105
	ds_read_b64_tr_b16 v[102:103], v3 offset:35840
	ds_read_b64_tr_b16 v[104:105], v3 offset:36352
	v_add_f32_e32 v5, v108, v5
	v_add_f32_e32 v5, v109, v5
	v_add_f32_e32 v5, v110, v5
	v_add_f32_e32 v5, v111, v5
	v_cvt_pk_bf16_f32 v162, v106, v107
	v_cvt_pk_bf16_f32 v163, v108, v109
	s_waitcnt lgkmcnt(14)
	v_mfma_f32_32x32x16_bf16 v[66:81], v[138:141], v[8:11], v[66:81]
	ds_read_b64_tr_b16 v[106:107], v3 offset:39936
	ds_read_b64_tr_b16 v[108:109], v3 offset:40448
	v_add_f32_e32 v3, v112, v5
	v_add_f32_e32 v3, v113, v3
	v_add_f32_e32 v3, 0, v3
	v_cvt_pk_bf16_f32 v164, v110, v111
	v_cvt_pk_bf16_f32 v165, v112, v113
	s_nop 0
	v_add_f32_e32 v110, v4, v3
	s_waitcnt lgkmcnt(14)
	v_mfma_f32_32x32x16_bf16 v[34:49], v[178:181], v[82:85], v[34:49]
	s_nop 0
	v_exp_f32_e32 v66, v66
	v_exp_f32_e32 v67, v67
	v_exp_f32_e32 v68, v68
	v_exp_f32_e32 v69, v69
	v_mov_b32_e32 v74, v6
	v_mov_b32_e32 v75, v6
	v_mov_b32_e32 v76, v6
	v_mov_b32_e32 v77, v6
	v_mov_b32_e32 v78, v6
	v_mov_b32_e32 v79, v6
	v_mov_b32_e32 v80, v6
	v_mov_b32_e32 v81, v6
	s_waitcnt lgkmcnt(12)
	v_mfma_f32_32x32x16_bf16 v[50:65], v[178:181], v[86:89], v[50:65]
	v_exp_f32_e32 v70, v70
	v_exp_f32_e32 v71, v71
	v_exp_f32_e32 v72, v72
	v_exp_f32_e32 v73, v73
	s_waitcnt lgkmcnt(10)
	v_mfma_f32_32x32x16_bf16 v[34:49], v[170:173], v[90:93], v[34:49]
	v_exp_f32_e32 v74, v74
	v_exp_f32_e32 v75, v75
	v_exp_f32_e32 v76, v76
	v_exp_f32_e32 v77, v77
	s_waitcnt lgkmcnt(8)
	v_mfma_f32_32x32x16_bf16 v[50:65], v[170:173], v[94:97], v[50:65]
	v_exp_f32_e32 v78, v78
	v_exp_f32_e32 v79, v79
	v_exp_f32_e32 v80, v80
	v_exp_f32_e32 v81, v81
	s_waitcnt lgkmcnt(6)
	v_mfma_f32_32x32x16_bf16 v[34:49], v[166:169], v[114:117], v[34:49]
	v_mov_b32_e32 v16, v6
	v_mov_b32_e32 v17, v6
	v_mov_b32_e32 v3, v2
	v_mov_b32_e32 v4, v2
	v_mov_b32_e32 v5, v2
	v_mov_b32_e32 v7, v6
	v_mov_b32_e32 v8, v6
	v_mov_b32_e32 v9, v6
	v_mov_b32_e32 v10, v6
	v_mov_b32_e32 v11, v6
	v_mov_b32_e32 v12, v6
	v_mov_b32_e32 v13, v6
	v_mov_b32_e32 v14, v6
	v_mov_b32_e32 v15, v6
	v_mov_b64_e32 v[96:97], v[16:17]
	v_mov_b64_e32 v[94:95], v[14:15]
	v_mov_b64_e32 v[92:93], v[12:13]
	v_mov_b64_e32 v[90:91], v[10:11]
	v_mov_b64_e32 v[88:89], v[8:9]
	v_mov_b64_e32 v[86:87], v[6:7]
	v_mov_b64_e32 v[84:85], v[4:5]
	v_mov_b64_e32 v[82:83], v[2:3]
	s_waitcnt lgkmcnt(4)
	v_mfma_f32_32x32x16_bf16 v[50:65], v[166:169], v[98:101], v[50:65]
	v_exp_f32_e32 v86, v86
	v_exp_f32_e32 v87, v87
	v_exp_f32_e32 v88, v88
	v_exp_f32_e32 v89, v89
	s_waitcnt lgkmcnt(2)
	v_mfma_f32_32x32x16_bf16 v[34:49], v[162:165], v[102:105], v[34:49]
	v_exp_f32_e32 v90, v90
	v_exp_f32_e32 v91, v91
	v_exp_f32_e32 v92, v92
	v_exp_f32_e32 v93, v93
	s_waitcnt lgkmcnt(0)
	v_mfma_f32_32x32x16_bf16 v[50:65], v[162:165], v[106:109], v[50:65]
	v_exp_f32_e32 v94, v94
	v_exp_f32_e32 v95, v95
	v_exp_f32_e32 v96, v96
	v_exp_f32_e32 v97, v97
	v_add_f32_e32 v3, v66, v67
	v_add_f32_e32 v3, v68, v3
	v_add_f32_e32 v3, v69, v3
	v_add_f32_e32 v3, v70, v3
	v_add_f32_e32 v3, v71, v3
	v_add_f32_e32 v3, v72, v3
	v_add_f32_e32 v3, v73, v3
	v_add_f32_e32 v3, v74, v3
	v_add_f32_e32 v3, v75, v3
	v_add_f32_e32 v3, v76, v3
	v_add_f32_e32 v3, v77, v3
	v_add_f32_e32 v3, v78, v3
	v_add_f32_e32 v3, v79, v3
	v_add_f32_e32 v3, v80, v3
	v_add_f32_e32 v3, v81, v3
	v_add_f32_e32 v3, v82, v3
	v_add_f32_e32 v3, v83, v3
	v_add_f32_e32 v3, v84, v3
	v_add_f32_e32 v3, v85, v3
	v_add_f32_e32 v3, v86, v3
	v_add_f32_e32 v3, v87, v3
	v_add_f32_e32 v3, v88, v3
	v_add_f32_e32 v3, v89, v3
	v_add_f32_e32 v3, v90, v3
	v_add_f32_e32 v3, v91, v3
	v_add_f32_e32 v3, v92, v3
	v_add_f32_e32 v3, v93, v3
	v_add_f32_e32 v3, v94, v3
	v_add_f32_e32 v3, v95, v3
	s_waitcnt vmcnt(0) lgkmcnt(0)
	s_barrier
	v_add_f32_e32 v3, v96, v3
	v_add_f32_e32 v3, v97, v3
	v_add_f32_e32 v3, v110, v3
	v_cvt_pk_bf16_f32 v8, v66, v67
	v_cvt_pk_bf16_f32 v9, v68, v69
	v_cvt_pk_bf16_f32 v10, v70, v71
	v_cvt_pk_bf16_f32 v11, v72, v73
	v_cvt_pk_bf16_f32 v12, v74, v75
	v_cvt_pk_bf16_f32 v13, v76, v77
	v_cvt_pk_bf16_f32 v14, v78, v79
	v_cvt_pk_bf16_f32 v15, v80, v81
	v_cvt_pk_bf16_f32 v98, v82, v83
	v_cvt_pk_bf16_f32 v99, v84, v85
	v_cvt_pk_bf16_f32 v100, v86, v87
	v_cvt_pk_bf16_f32 v101, v88, v89
	v_cvt_pk_bf16_f32 v102, v90, v91
	v_cvt_pk_bf16_f32 v103, v92, v93
	v_cvt_pk_bf16_f32 v104, v94, v95
	v_cvt_pk_bf16_f32 v105, v96, v97
	v_add3_u32 v4, v218, v217, s24
	ds_read_b64_tr_b16 v[66:67],v4 offset:0
	ds_read_b64_tr_b16 v[68:69],v4 offset:512
	ds_read_b64_tr_b16 v[70:71],v4 offset:1024
	ds_read_b64_tr_b16 v[72:73],v4 offset:1536
	ds_read_b64_tr_b16 v[74:75],v4 offset:2048
	ds_read_b64_tr_b16 v[76:77],v4 offset:2560
	ds_read_b64_tr_b16 v[78:79],v4 offset:3072
	ds_read_b64_tr_b16 v[80:81],v4 offset:3584
	s_waitcnt lgkmcnt(0)
	s_nop 0
	v_mfma_f32_32x32x16_bf16 v[34:49], v[8:11], v[66:69], v[34:49]
	ds_read_b64_tr_b16 v[66:67],v4 offset:4096
	ds_read_b64_tr_b16 v[68:69],v4 offset:4608
	v_mfma_f32_32x32x16_bf16 v[34:49], v[12:15], v[70:73], v[34:49]
	ds_read_b64_tr_b16 v[70:71],v4 offset:5120
	ds_read_b64_tr_b16 v[72:73],v4 offset:5632
	v_mfma_f32_32x32x16_bf16 v[34:49], v[98:101], v[74:77], v[34:49]
	ds_read_b64_tr_b16 v[74:75],v4 offset:6144
	ds_read_b64_tr_b16 v[76:77],v4 offset:6656
	ds_read_b64_tr_b16 v[82:83],v4 offset:7168
	ds_read_b64_tr_b16 v[84:85],v4 offset:7680
	s_waitcnt lgkmcnt(0)
	v_mfma_f32_32x32x16_bf16 v[34:49], v[102:105], v[78:81], v[34:49]
	v_mfma_f32_32x32x16_bf16 v[50:65], v[8:11], v[66:69], v[50:65]
	v_mov_b32_e32 v4, v3
	s_nop 1
	v_permlane32_swap_b32_e32 v3, v4
	v_cmp_gt_u32_e32 vcc, 32, v1
	v_mfma_f32_32x32x16_bf16 v[50:65], v[12:15], v[70:73], v[50:65]
	v_mfma_f32_32x32x16_bf16 v[50:65], v[98:101], v[74:77], v[50:65]
	v_mfma_f32_32x32x16_bf16 v[50:65], v[102:105], v[82:85], v[50:65]
	s_and_saveexec_b64 s[24:25], vcc
	s_cbranch_execz .LBB0_1117
	v_lshl_add_u32 v5, v215, 2, s27
	v_add_f32_e32 v3, v3, v4
	ds_write_b32 v5, v3 offset:128
	s_branch .LBB0_1117
